# attention: LDS tile write placed after PV MFMA 19 instead of 15
# speedup vs baseline: 1.0066x; 1.0066x over previous
; __device__ __forceinline__ void attn_phase(const LArgs& a, LAS unsigned char* lds) {
;     ...
;         for (int j = 0; j < NT; ++j) {
;             const int cur = j & 1;
;             if (j + 1 < NT) ATT_LOAD(j + 1);
;             if (late && j > 0) ATT_PV(vprev, 0);
;             const LAS unsigned char* kb_ = lds + cur * KBUF;
;             f32x16 s[2];
; #pragma unroll
;             for (int kb = 0; kb < 2; ++kb) {
; #pragma unroll
;                 for (int r = 0; r < 16; ++r) s[kb][r] = 0.f;
; #pragma unroll
;                 for (int ks = 0; ks < 4; ++ks) { const bf16x8 kf = *(const LAS bf16x8*)(kb_ + (32 * kb + kappa) * KROW + mp * 128 + ks * 32 + hi * 16);
;                     s[kb] = __builtin_amdgcn_mfma_f32_32x32x16_bf16(kf, qf[ks], s[kb], 0, 0, 0); }
;             }
;             if (!late) ATT_PV_PRE(vcur);
;             float mx = s[0][0];
; #pragma unroll
;             for (int r = 1; r < 16; ++r) mx = fmaxf(mx, s[0][r]);
; #pragma unroll
;             for (int r = 0; r < 16; ++r) mx = fmaxf(mx, s[1][r]);
;             mx = fmaxf(mx, xor32_get(mx, xaddr));
;             const float mnew = fmaxf(mrun, mx);
;             if (__any(mnew > mrun)) {
;                 const float alpha = __builtin_amdgcn_exp2f(mrun - mnew); lrun *= alpha;
; #pragma unroll
;                 for (int d = 0; d < 4; ++d)
; #pragma unroll
;                     for (int r = 0; r < 16; ++r) o[d][r] *= alpha;
;                 mrun = mnew;
;             }
;             float psum = 0.f;
; #pragma unroll
;             for (int kb = 0; kb < 2; ++kb)
; #pragma unroll
;                 for (int r = 0; r < 16; ++r) { const float pv = __builtin_amdgcn_exp2f(s[kb][r] - mrun); s[kb][r] = pv; psum += pv; }
;             lrun += psum;
; #pragma unroll
;             for (int kb = 0; kb < 2; ++kb)
; #pragma unroll
;                 for (int g = 0; g < 2; ++g) {
;                     u32x4 w4; w4.x = pg8::cvt_pk_bf16(s[kb][8 * g + 0], s[kb][8 * g + 1]); w4.y = pg8::cvt_pk_bf16(s[kb][8 * g + 2], s[kb][8 * g + 3]);
;                     w4.z = pg8::cvt_pk_bf16(s[kb][8 * g + 4], s[kb][8 * g + 5]); w4.w = pg8::cvt_pk_bf16(s[kb][8 * g + 6], s[kb][8 * g + 7]);
;                     pw[2 * kb + g] = w4;
;                 }
;             if (!late) ATT_PV(vcur, 1);
;             if (j + 1 < NT) ATT_STORE(cur ^ 1, vnext);
;             __syncthreads();
.Lattn_noload:
	s_and_b32 s23, s21, 1
	s_mul_i32 s16, s23, 0x4400
	s_mul_i32 s24, s22, 0x4800
	v_add_u32_e32 v252, s16, v171
	v_add3_u32 v218, s24, v148, v178
	ds_read_b128 v[96:99], v252
	ds_read_b128 v[100:103], v252 offset:32
	ds_read_b128 v[104:107], v252 offset:64
	ds_read_b128 v[108:111], v252 offset:96
	ds_read_b128 v[182:185], v252 offset:8704
	ds_read_b128 v[186:189], v252 offset:8736
	ds_read_b128 v[224:227], v252 offset:8768
	ds_read_b128 v[244:247], v252 offset:8800
	ds_read_b128 v[174:177], v218 offset:34816
	ds_read_b128 v[248:251], v218 offset:39424
	s_waitcnt lgkmcnt(9)
	v_mfma_f32_32x32x16_bf16 v[228:243], v[96:99], v[112:115], v[202:217]
	ds_read_b128 v[96:99], v218 offset:44032
	s_waitcnt lgkmcnt(9)
	v_mfma_f32_32x32x16_bf16 v[228:243], v[100:103], v[116:119], v[228:243]
	ds_read_b128 v[100:103], v218 offset:48640
	s_waitcnt lgkmcnt(9)
	v_mfma_f32_32x32x16_bf16 v[228:243], v[104:107], v[120:123], v[228:243]
	ds_read_b128 v[104:107], v218 offset:34848
	s_waitcnt lgkmcnt(9)
	v_mfma_f32_32x32x16_bf16 v[228:243], v[108:111], v[124:127], v[228:243]
	ds_read_b128 v[108:111], v218 offset:39456
	s_waitcnt lgkmcnt(9)
	v_mfma_f32_32x32x16_bf16 v[64:79], v[182:185], v[112:115], v[202:217]
	ds_read_b128 v[182:185], v218 offset:44064
	s_waitcnt lgkmcnt(9)
	v_mfma_f32_32x32x16_bf16 v[64:79], v[186:189], v[116:119], v[64:79]
	ds_read_b128 v[186:189], v218 offset:48672
	s_waitcnt lgkmcnt(9)
	v_mfma_f32_32x32x16_bf16 v[64:79], v[224:227], v[120:123], v[64:79]
	ds_read_b128 v[224:227], v218 offset:34880
	s_waitcnt lgkmcnt(9)
	v_mfma_f32_32x32x16_bf16 v[64:79], v[244:247], v[124:127], v[64:79]
	ds_read_b128 v[244:247], v218 offset:39488
	s_waitcnt lgkmcnt(9)
	v_mfma_f32_32x32x16_bf16 v[48:63], v[174:177], v[92:95], v[48:63]
	ds_read_b128 v[174:177], v218 offset:44096
	v_exp_f32_e32 v228, v228
	v_exp_f32_e32 v229, v229
	v_exp_f32_e32 v230, v230
	s_waitcnt lgkmcnt(9)
	v_mfma_f32_32x32x16_bf16 v[32:47], v[248:251], v[92:95], v[32:47]
	ds_read_b128 v[248:251], v218 offset:48704
	v_exp_f32_e32 v231, v231
	v_exp_f32_e32 v232, v232
	v_exp_f32_e32 v233, v233
	s_waitcnt lgkmcnt(9)
	v_mfma_f32_32x32x16_bf16 v[16:31], v[96:99], v[92:95], v[16:31]
	ds_read_b128 v[96:99], v218 offset:34912
	v_exp_f32_e32 v234, v234
	v_exp_f32_e32 v235, v235
	v_exp_f32_e32 v236, v236
	s_waitcnt lgkmcnt(9)
	v_mfma_f32_32x32x16_bf16 v[0:15], v[100:103], v[92:95], v[0:15]
	ds_read_b128 v[100:103], v218 offset:39520
	v_exp_f32_e32 v237, v237
	v_exp_f32_e32 v238, v238
	v_exp_f32_e32 v239, v239
	s_waitcnt lgkmcnt(9)
	v_mfma_f32_32x32x16_bf16 v[48:63], v[104:107], v[88:91], v[48:63]
	ds_read_b128 v[104:107], v218 offset:44128
	v_exp_f32_e32 v240, v240
	v_exp_f32_e32 v241, v241
	v_exp_f32_e32 v242, v242
	s_waitcnt lgkmcnt(9)
	v_mfma_f32_32x32x16_bf16 v[32:47], v[108:111], v[88:91], v[32:47]
	ds_read_b128 v[108:111], v218 offset:48736
	v_exp_f32_e32 v243, v243
	v_exp_f32_e32 v64, v64
	v_add_f32_e32 v190, v228, v229
	v_add_f32_e32 v190, v190, v230
	s_waitcnt lgkmcnt(9)
	v_mfma_f32_32x32x16_bf16 v[16:31], v[182:185], v[88:91], v[16:31]
	v_exp_f32_e32 v65, v65
	v_add_f32_e32 v190, v190, v231
	v_add_f32_e32 v190, v190, v232
	v_exp_f32_e32 v66, v66
	v_add_f32_e32 v190, v190, v233
	s_waitcnt lgkmcnt(8)
	v_mfma_f32_32x32x16_bf16 v[0:15], v[186:189], v[88:91], v[0:15]
	v_add_f32_e32 v190, v190, v234
	v_exp_f32_e32 v67, v67
	v_add_f32_e32 v190, v190, v235
	v_add_f32_e32 v190, v190, v236
	v_exp_f32_e32 v68, v68
	s_waitcnt lgkmcnt(7)
	v_mfma_f32_32x32x16_bf16 v[48:63], v[224:227], v[84:87], v[48:63]
	v_add_f32_e32 v190, v190, v237
	v_add_f32_e32 v190, v190, v238
	v_exp_f32_e32 v69, v69
	v_add_f32_e32 v190, v190, v239
	v_add_f32_e32 v190, v190, v240
	s_waitcnt lgkmcnt(6)
	v_mfma_f32_32x32x16_bf16 v[32:47], v[244:247], v[84:87], v[32:47]
	v_exp_f32_e32 v70, v70
	v_add_f32_e32 v190, v190, v241
	v_add_f32_e32 v190, v190, v242
	v_exp_f32_e32 v71, v71
	v_add_f32_e32 v190, v190, v243
	s_waitcnt lgkmcnt(5)
	v_mfma_f32_32x32x16_bf16 v[16:31], v[174:177], v[84:87], v[16:31]
	v_exp_f32_e32 v72, v72
	v_exp_f32_e32 v73, v73
	v_exp_f32_e32 v74, v74
	s_waitcnt lgkmcnt(4)
	v_mfma_f32_32x32x16_bf16 v[0:15], v[248:251], v[84:87], v[0:15]
	v_exp_f32_e32 v75, v75
	v_exp_f32_e32 v76, v76
	v_exp_f32_e32 v77, v77
	s_andn2_b64 vcc, exec, s[0:1]
	s_cbranch_vccnz .Lattn_nowrite
	s_xor_b32 s0, s23, 1
	s_mulk_i32 s0, 0x4400
	s_mul_i32 s1, s20, 0x4800
	v_add_u32_e32 v219, s0, v168
	s_waitcnt vmcnt(3)
	ds_write_b128 v219, v[128:131]
	s_waitcnt vmcnt(2)
	ds_write_b128 v219, v[132:135] offset:8704
	v_add_u32_e32 v219, s1, v169
	s_waitcnt vmcnt(1)
	ds_write_b128 v219, v[136:139] offset:34816
	s_waitcnt vmcnt(0)
	ds_write_b128 v219, v[140:143] offset:44032
.Lattn_nowrite:
	s_waitcnt lgkmcnt(3)
	v_mfma_f32_32x32x16_bf16 v[48:63], v[96:99], v[80:83], v[48:63]
	v_exp_f32_e32 v78, v78
	v_exp_f32_e32 v79, v79
	v_cvt_pk_bf16_f32 v92, v228, v229
	v_cvt_pk_bf16_f32 v93, v230, v231
	v_cvt_pk_bf16_f32 v94, v232, v233
	s_waitcnt lgkmcnt(2)
	v_mfma_f32_32x32x16_bf16 v[32:47], v[100:103], v[80:83], v[32:47]
	v_cvt_pk_bf16_f32 v95, v234, v235
	v_cvt_pk_bf16_f32 v88, v236, v237
	v_cvt_pk_bf16_f32 v89, v238, v239
	v_cvt_pk_bf16_f32 v90, v240, v241
	v_cvt_pk_bf16_f32 v91, v242, v243
	v_add_f32_e32 v191, v64, v65
	v_add_f32_e32 v191, v191, v66
	s_waitcnt lgkmcnt(1)
	v_mfma_f32_32x32x16_bf16 v[16:31], v[104:107], v[80:83], v[16:31]
	v_add_f32_e32 v191, v191, v67
	v_add_f32_e32 v191, v191, v68
	v_add_f32_e32 v191, v191, v69
	v_add_f32_e32 v191, v191, v70
	v_add_f32_e32 v191, v191, v71
	v_add_f32_e32 v191, v191, v72
	v_add_f32_e32 v191, v191, v73
	s_waitcnt lgkmcnt(0)
	v_mfma_f32_32x32x16_bf16 v[0:15], v[108:111], v[80:83], v[0:15]
	v_add_f32_e32 v191, v191, v74
	v_add_f32_e32 v191, v191, v75
	v_add_f32_e32 v191, v191, v76
	v_add_f32_e32 v191, v191, v77
	v_add_f32_e32 v191, v191, v78
	v_add_f32_e32 v191, v191, v79
	v_add_f32_e32 v190, v190, v191
	v_cvt_pk_bf16_f32 v84, v64, v65
	v_cvt_pk_bf16_f32 v85, v66, v67
	v_cvt_pk_bf16_f32 v86, v68, v69
	v_cvt_pk_bf16_f32 v87, v70, v71
	v_cvt_pk_bf16_f32 v80, v72, v73
	v_cvt_pk_bf16_f32 v81, v74, v75
	v_cvt_pk_bf16_f32 v82, v76, v77
	v_cvt_pk_bf16_f32 v83, v78, v79
	v_cmp_lt_f32_e32 vcc, 0x43800000, v190
	s_cbranch_vccnz .Lattn_rare
	v_add_f32_e32 v149, v149, v190
